# softmax-sum exchange between the lane halves by v_permlane32_swap instead of ds_bpermute in the attention finalisations
# baseline (speedup 1.0000x reference)
; __device__ __forceinline__ void phase4_attn(const Args& a, LAS unsigned char* lds) {
;     ...
;                     ls += __shfl_xor(ls, 32);
;                     const float inv = 1.f / fmaxf(ls, 1e-20f);
; #pragma unroll
;                     for (int mt = 0; mt < 4; ++mt) s4[mt] *= inv;
;                     if (t >= 16) {
;                         float oprev = 0.f;
; #pragma unroll
;                         for (int idx = 0; idx < 16; ++idx) {
;                             const int mt = idx >> 2, ap = idx & 3;
;                             const float tail = 0.5f * s4[mt][4 * ap + 3];
;                             const float ot = __shfl_xor(tail, 32);
;                             const float inner = s4[mt][4 * ap] + s4[mt][4 * ap + 1] + s4[mt][4 * ap + 2] + tail;
;                             const float prev = h ? ot : oprev;
;                             oprev = ot;
;                             IMP[(g * 64 + ql) * A_IMPSTR + 8 * mt + 2 * ap + h] = inner + prev;
;                         }
.Lc0_fin:
	v_add_f32_e32 v232, v232, v233
	v_mov_b32_e32 v239, v232
	s_nop 1
	v_permlane32_swap_b32 v232, v239
	s_waitcnt lgkmcnt(0)
	v_add_f32_e32 v239, v232, v239
	v_max_f32_e32 v239, 0x1e3ce508, v239
	v_div_scale_f32 v240, s[44:45], v239, v239, 1.0
	v_rcp_f32_e32 v241, v240
	v_div_scale_f32 v242, vcc, 1.0, v239, 1.0
	s_nop 0
	v_fma_f32 v243, -v240, v241, 1.0
	v_fmac_f32_e32 v241, v243, v241
	v_mul_f32_e32 v243, v242, v241
	v_fma_f32 v237, -v240, v243, v242
	v_fmac_f32_e32 v243, v237, v241
	v_fma_f32 v240, -v240, v243, v242
	v_div_fmas_f32 v240, v240, v241, v243
	v_div_fixup_f32 v238, v240, v239, 1.0
	v_mul_f32_e32 v0, v0, v238
	v_mul_f32_e32 v1, v1, v238
	v_mul_f32_e32 v2, v2, v238
	v_mul_f32_e32 v3, v3, v238
	v_mul_f32_e32 v4, v4, v238
	v_mul_f32_e32 v5, v5, v238
	v_mul_f32_e32 v6, v6, v238
	v_mul_f32_e32 v7, v7, v238
	v_mul_f32_e32 v8, v8, v238
	v_mul_f32_e32 v9, v9, v238
	v_mul_f32_e32 v10, v10, v238
	v_mul_f32_e32 v11, v11, v238
	v_mul_f32_e32 v12, v12, v238
	v_mul_f32_e32 v13, v13, v238
	v_mul_f32_e32 v14, v14, v238
	v_mul_f32_e32 v15, v15, v238
	v_mul_f32_e32 v16, v16, v238
	v_mul_f32_e32 v17, v17, v238
	v_mul_f32_e32 v18, v18, v238
	v_mul_f32_e32 v19, v19, v238
	v_mul_f32_e32 v20, v20, v238
	v_mul_f32_e32 v21, v21, v238
	v_mul_f32_e32 v22, v22, v238
	v_mul_f32_e32 v23, v23, v238
	v_mul_f32_e32 v24, v24, v238
	v_mul_f32_e32 v25, v25, v238
	v_mul_f32_e32 v26, v26, v238
	v_mul_f32_e32 v27, v27, v238
	v_mul_f32_e32 v28, v28, v238
	v_mul_f32_e32 v29, v29, v238
	v_mul_f32_e32 v30, v30, v238
	v_mul_f32_e32 v31, v31, v238
	s_cmp_gt_u32 s38, 15
	s_cbranch_scc0 .Lc0_noimp
	v_cmp_ne_u32_e64 s[46:47], 0, v101
	ds_bpermute_b32 v32, v193, v176
	ds_bpermute_b32 v33, v193, v177
	ds_bpermute_b32 v34, v193, v178
	ds_bpermute_b32 v35, v193, v179
	ds_bpermute_b32 v36, v193, v180
	ds_bpermute_b32 v37, v193, v181
	ds_bpermute_b32 v38, v193, v182
	ds_bpermute_b32 v39, v193, v183
	ds_bpermute_b32 v40, v193, v246
	ds_bpermute_b32 v41, v193, v247
	ds_bpermute_b32 v42, v193, v248
	ds_bpermute_b32 v43, v193, v249
	ds_bpermute_b32 v44, v193, v250
	ds_bpermute_b32 v45, v193, v251
	ds_bpermute_b32 v46, v193, v252
	ds_bpermute_b32 v47, v193, v253
	v_lshrrev_b32_e32 v48, 7, v152
	v_lshl_or_b32 v48, v48, 6, v98
	v_mul_u32_u24_e32 v48, 0x84, v48
	v_add_u32_e32 v48, v48, v155
	v_add_u32_e32 v48, 0x19e00, v48
	s_waitcnt lgkmcnt(0)
	v_cndmask_b32_e64 v49, 0, v32, s[46:47]
	v_add_f32_e32 v49, v160, v49
	v_mul_f32_e32 v49, v49, v238
	ds_write_b32 v48, v49 offset:0
	v_cndmask_b32_e64 v50, v32, v33, s[46:47]
	v_add_f32_e32 v50, v161, v50
	v_mul_f32_e32 v50, v50, v238
	ds_write_b32 v48, v50 offset:8
	v_cndmask_b32_e64 v49, v33, v34, s[46:47]
	v_add_f32_e32 v49, v162, v49
	v_mul_f32_e32 v49, v49, v238
	ds_write_b32 v48, v49 offset:16
	v_cndmask_b32_e64 v50, v34, v35, s[46:47]
	v_add_f32_e32 v50, v163, v50
	v_mul_f32_e32 v50, v50, v238
	ds_write_b32 v48, v50 offset:24
	v_cndmask_b32_e64 v49, v35, v36, s[46:47]
	v_add_f32_e32 v49, v164, v49
	v_mul_f32_e32 v49, v49, v238
	ds_write_b32 v48, v49 offset:32
	v_cndmask_b32_e64 v50, v36, v37, s[46:47]
	v_add_f32_e32 v50, v165, v50
	v_mul_f32_e32 v50, v50, v238
	ds_write_b32 v48, v50 offset:40
	v_cndmask_b32_e64 v49, v37, v38, s[46:47]
	v_add_f32_e32 v49, v166, v49
	v_mul_f32_e32 v49, v49, v238
	ds_write_b32 v48, v49 offset:48
	v_cndmask_b32_e64 v50, v38, v39, s[46:47]
	v_add_f32_e32 v50, v167, v50
	v_mul_f32_e32 v50, v50, v238
	ds_write_b32 v48, v50 offset:56
	v_cndmask_b32_e64 v49, v39, v40, s[46:47]
	v_add_f32_e32 v49, v168, v49
	v_mul_f32_e32 v49, v49, v238
	ds_write_b32 v48, v49 offset:64
	v_cndmask_b32_e64 v50, v40, v41, s[46:47]
	v_add_f32_e32 v50, v169, v50
	v_mul_f32_e32 v50, v50, v238
	ds_write_b32 v48, v50 offset:72
	v_cndmask_b32_e64 v49, v41, v42, s[46:47]
	v_add_f32_e32 v49, v170, v49
	v_mul_f32_e32 v49, v49, v238
	ds_write_b32 v48, v49 offset:80
	v_cndmask_b32_e64 v50, v42, v43, s[46:47]
	v_add_f32_e32 v50, v171, v50
	v_mul_f32_e32 v50, v50, v238
	ds_write_b32 v48, v50 offset:88
	v_cndmask_b32_e64 v49, v43, v44, s[46:47]
	v_add_f32_e32 v49, v172, v49
	v_mul_f32_e32 v49, v49, v238
	ds_write_b32 v48, v49 offset:96
	v_cndmask_b32_e64 v50, v44, v45, s[46:47]
	v_add_f32_e32 v50, v173, v50
	v_mul_f32_e32 v50, v50, v238
	ds_write_b32 v48, v50 offset:104
	v_cndmask_b32_e64 v49, v45, v46, s[46:47]
	v_add_f32_e32 v49, v174, v49
	v_mul_f32_e32 v49, v49, v238
	ds_write_b32 v48, v49 offset:112
	v_cndmask_b32_e64 v50, v46, v47, s[46:47]
	v_add_f32_e32 v50, v175, v50
	v_mul_f32_e32 v50, v50, v238
	ds_write_b32 v48, v50 offset:120

; __device__ __forceinline__ void phase4_attn(const Args& a, LAS unsigned char* lds) {
;     ...
;                     if (i == n_sel - 1 || i == n_all - 1) { const float lt = l_run + __shfl_xor(l_run, 32); const float sc = ((i == n_sel - 1) ? g1 : g2) / fmaxf(lt, 1e-20f);
;                         comb[hkv][0] += oacc[0] * sc; comb[hkv][1] += oacc[1] * sc; oacc[0] = zero16(); oacc[1] = zero16(); l_run = 0.f; }
.Lt1_fin:
	v_mov_b32_e32 v75, v112
	s_nop 1
	v_permlane32_swap_b32 v112, v75
	s_waitcnt lgkmcnt(0)
	v_add_f32_e32 v75, v112, v75
	v_max_f32_e32 v75, 0x1e3ce508, v75
	v_div_scale_f32 v78, s[4:5], v75, v75, v76
	v_rcp_f32_e32 v79, v78
	v_div_scale_f32 v241, vcc, v76, v75, v76
	v_mov_b32_e32 v112, 0
	v_fma_f32 v242, -v78, v79, 1.0
	v_fmac_f32_e32 v79, v242, v79
	v_mul_f32_e32 v242, v241, v79
	v_fma_f32 v243, -v78, v242, v241
	v_fmac_f32_e32 v242, v243, v79
	v_fma_f32 v78, -v78, v242, v241
	v_div_fmas_f32 v78, v78, v79, v242
	v_div_fixup_f32 v76, v78, v75, v76
	v_pk_fma_f32 v[148:149], v[0:1], v[76:77], v[148:149] op_sel_hi:[1,0,1]
	v_pk_fma_f32 v[150:151], v[2:3], v[76:77], v[150:151] op_sel_hi:[1,0,1]
	v_pk_fma_f32 v[146:147], v[4:5], v[76:77], v[146:147] op_sel_hi:[1,0,1]
	v_pk_fma_f32 v[144:145], v[6:7], v[76:77], v[144:145] op_sel_hi:[1,0,1]
	v_pk_fma_f32 v[142:143], v[8:9], v[76:77], v[142:143] op_sel_hi:[1,0,1]
	v_pk_fma_f32 v[140:141], v[10:11], v[76:77], v[140:141] op_sel_hi:[1,0,1]
	v_pk_fma_f32 v[138:139], v[12:13], v[76:77], v[138:139] op_sel_hi:[1,0,1]
	v_pk_fma_f32 v[132:133], v[14:15], v[76:77], v[132:133] op_sel_hi:[1,0,1]
	v_pk_fma_f32 v[134:135], v[16:17], v[76:77], v[134:135] op_sel_hi:[1,0,1]
	v_pk_fma_f32 v[136:137], v[18:19], v[76:77], v[136:137] op_sel_hi:[1,0,1]
	v_pk_fma_f32 v[130:131], v[20:21], v[76:77], v[130:131] op_sel_hi:[1,0,1]
	v_pk_fma_f32 v[128:129], v[22:23], v[76:77], v[128:129] op_sel_hi:[1,0,1]
	v_pk_fma_f32 v[126:127], v[24:25], v[76:77], v[126:127] op_sel_hi:[1,0,1]
	v_pk_fma_f32 v[124:125], v[26:27], v[76:77], v[124:125] op_sel_hi:[1,0,1]
	v_pk_fma_f32 v[122:123], v[28:29], v[76:77], v[122:123] op_sel_hi:[1,0,1]
	v_pk_fma_f32 v[120:121], v[30:31], v[76:77], v[120:121] op_sel_hi:[1,0,1]
	v_mov_b32_e32 v0, 0
	v_mov_b32_e32 v1, 0
	v_mov_b32_e32 v2, 0
	v_mov_b32_e32 v3, 0
	v_mov_b32_e32 v4, 0
	v_mov_b32_e32 v5, 0
	v_mov_b32_e32 v6, 0
	v_mov_b32_e32 v7, 0
	v_mov_b32_e32 v8, 0
	v_mov_b32_e32 v9, 0
	v_mov_b32_e32 v10, 0
	v_mov_b32_e32 v11, 0
	v_mov_b32_e32 v12, 0
	v_mov_b32_e32 v13, 0
	v_mov_b32_e32 v14, 0
	v_mov_b32_e32 v15, 0
	v_mov_b32_e32 v16, 0
	v_mov_b32_e32 v17, 0
	v_mov_b32_e32 v18, 0
	v_mov_b32_e32 v19, 0
	v_mov_b32_e32 v20, 0
	v_mov_b32_e32 v21, 0
	v_mov_b32_e32 v22, 0
	v_mov_b32_e32 v23, 0
	v_mov_b32_e32 v24, 0
	v_mov_b32_e32 v25, 0
	v_mov_b32_e32 v26, 0
	v_mov_b32_e32 v27, 0
	v_mov_b32_e32 v28, 0
	v_mov_b32_e32 v29, 0
	v_mov_b32_e32 v30, 0
	v_mov_b32_e32 v31, 0
	s_branch .Lt1_stage

; __device__ __forceinline__ void phase4_attn(const Args& a, LAS unsigned char* lds) {
;     ...
;                     ls += __shfl_xor(ls, 32);
;                     const float inv = 1.f / fmaxf(ls, 1e-20f);
; #pragma unroll
;                     for (int mt = 0; mt < 4; ++mt) s4[mt] *= inv;
;                     if (t >= 16) {
;                         float oprev = 0.f;
; #pragma unroll
;                         for (int idx = 0; idx < 16; ++idx) {
;                             const int mt = idx >> 2, ap = idx & 3;
;                             const float tail = 0.5f * s4[mt][4 * ap + 3];
;                             const float ot = __shfl_xor(tail, 32);
;                             const float inner = s4[mt][4 * ap] + s4[mt][4 * ap + 1] + s4[mt][4 * ap + 2] + tail;
;                             const float prev = h ? ot : oprev;
;                             oprev = ot;
;                             IMP[(g * 64 + ql) * A_IMPSTR + 8 * mt + 2 * ap + h] = inner + prev;
;                         }
.Lc1_fin:
	v_add_f32_e32 v232, v232, v233
	v_mov_b32_e32 v239, v232
	s_nop 1
	v_permlane32_swap_b32 v232, v239
	s_waitcnt lgkmcnt(0)
	v_add_f32_e32 v239, v232, v239
	v_max_f32_e32 v239, 0x1e3ce508, v239
	v_div_scale_f32 v240, s[44:45], v239, v239, 1.0
	v_rcp_f32_e32 v241, v240
	v_div_scale_f32 v242, vcc, 1.0, v239, 1.0
	s_nop 0
	v_fma_f32 v243, -v240, v241, 1.0
	v_fmac_f32_e32 v241, v243, v241
	v_mul_f32_e32 v243, v242, v241
	v_fma_f32 v237, -v240, v243, v242
	v_fmac_f32_e32 v243, v237, v241
	v_fma_f32 v240, -v240, v243, v242
	v_div_fmas_f32 v240, v240, v241, v243
	v_div_fixup_f32 v238, v240, v239, 1.0
	v_mul_f32_e32 v0, v0, v238
	v_mul_f32_e32 v1, v1, v238
	v_mul_f32_e32 v2, v2, v238
	v_mul_f32_e32 v3, v3, v238
	v_mul_f32_e32 v4, v4, v238
	v_mul_f32_e32 v5, v5, v238
	v_mul_f32_e32 v6, v6, v238
	v_mul_f32_e32 v7, v7, v238
	v_mul_f32_e32 v8, v8, v238
	v_mul_f32_e32 v9, v9, v238
	v_mul_f32_e32 v10, v10, v238
	v_mul_f32_e32 v11, v11, v238
	v_mul_f32_e32 v12, v12, v238
	v_mul_f32_e32 v13, v13, v238
	v_mul_f32_e32 v14, v14, v238
	v_mul_f32_e32 v15, v15, v238
	v_mul_f32_e32 v16, v16, v238
	v_mul_f32_e32 v17, v17, v238
	v_mul_f32_e32 v18, v18, v238
	v_mul_f32_e32 v19, v19, v238
	v_mul_f32_e32 v20, v20, v238
	v_mul_f32_e32 v21, v21, v238
	v_mul_f32_e32 v22, v22, v238
	v_mul_f32_e32 v23, v23, v238
	v_mul_f32_e32 v24, v24, v238
	v_mul_f32_e32 v25, v25, v238
	v_mul_f32_e32 v26, v26, v238
	v_mul_f32_e32 v27, v27, v238
	v_mul_f32_e32 v28, v28, v238
	v_mul_f32_e32 v29, v29, v238
	v_mul_f32_e32 v30, v30, v238
	v_mul_f32_e32 v31, v31, v238
	s_cmp_gt_u32 s38, 15
	s_cbranch_scc0 .Lc1_noimp
	v_cmp_ne_u32_e64 s[46:47], 0, v101
	ds_bpermute_b32 v32, v193, v176
	ds_bpermute_b32 v33, v193, v177
	ds_bpermute_b32 v34, v193, v178
	ds_bpermute_b32 v35, v193, v179
	ds_bpermute_b32 v36, v193, v180
	ds_bpermute_b32 v37, v193, v181
	ds_bpermute_b32 v38, v193, v182
	ds_bpermute_b32 v39, v193, v183
	ds_bpermute_b32 v40, v193, v246
	ds_bpermute_b32 v41, v193, v247
	ds_bpermute_b32 v42, v193, v248
	ds_bpermute_b32 v43, v193, v249
	ds_bpermute_b32 v44, v193, v250
	ds_bpermute_b32 v45, v193, v251
	ds_bpermute_b32 v46, v193, v252
	ds_bpermute_b32 v47, v193, v253
	v_lshrrev_b32_e32 v48, 7, v152
	v_lshl_or_b32 v48, v48, 6, v98
	v_mul_u32_u24_e32 v48, 0x84, v48
	v_add_u32_e32 v48, v48, v195
	v_add_u32_e32 v48, 0x19e00, v48
	s_waitcnt lgkmcnt(0)
	v_cndmask_b32_e64 v49, 0, v32, s[46:47]
	v_add_f32_e32 v49, v160, v49
	v_mul_f32_e32 v49, v49, v238
	ds_write_b32 v48, v49 offset:0
	v_cndmask_b32_e64 v50, v32, v33, s[46:47]
	v_add_f32_e32 v50, v161, v50
	v_mul_f32_e32 v50, v50, v238
	ds_write_b32 v48, v50 offset:8
	v_cndmask_b32_e64 v49, v33, v34, s[46:47]
	v_add_f32_e32 v49, v162, v49
	v_mul_f32_e32 v49, v49, v238
	ds_write_b32 v48, v49 offset:16
	v_cndmask_b32_e64 v50, v34, v35, s[46:47]
	v_add_f32_e32 v50, v163, v50
	v_mul_f32_e32 v50, v50, v238
	ds_write_b32 v48, v50 offset:24
	v_cndmask_b32_e64 v49, v35, v36, s[46:47]
	v_add_f32_e32 v49, v164, v49
	v_mul_f32_e32 v49, v49, v238
	ds_write_b32 v48, v49 offset:32
	v_cndmask_b32_e64 v50, v36, v37, s[46:47]
	v_add_f32_e32 v50, v165, v50
	v_mul_f32_e32 v50, v50, v238
	ds_write_b32 v48, v50 offset:40
	v_cndmask_b32_e64 v49, v37, v38, s[46:47]
	v_add_f32_e32 v49, v166, v49
	v_mul_f32_e32 v49, v49, v238
	ds_write_b32 v48, v49 offset:48
	v_cndmask_b32_e64 v50, v38, v39, s[46:47]
	v_add_f32_e32 v50, v167, v50
	v_mul_f32_e32 v50, v50, v238
	ds_write_b32 v48, v50 offset:56
	v_cndmask_b32_e64 v49, v39, v40, s[46:47]
	v_add_f32_e32 v49, v168, v49
	v_mul_f32_e32 v49, v49, v238
	ds_write_b32 v48, v49 offset:64
	v_cndmask_b32_e64 v50, v40, v41, s[46:47]
	v_add_f32_e32 v50, v169, v50
	v_mul_f32_e32 v50, v50, v238
	ds_write_b32 v48, v50 offset:72
	v_cndmask_b32_e64 v49, v41, v42, s[46:47]
	v_add_f32_e32 v49, v170, v49
	v_mul_f32_e32 v49, v49, v238
	ds_write_b32 v48, v49 offset:80
	v_cndmask_b32_e64 v50, v42, v43, s[46:47]
	v_add_f32_e32 v50, v171, v50
	v_mul_f32_e32 v50, v50, v238
	ds_write_b32 v48, v50 offset:88
	v_cndmask_b32_e64 v49, v43, v44, s[46:47]
	v_add_f32_e32 v49, v172, v49
	v_mul_f32_e32 v49, v49, v238
	ds_write_b32 v48, v49 offset:96
	v_cndmask_b32_e64 v50, v44, v45, s[46:47]
	v_add_f32_e32 v50, v173, v50
	v_mul_f32_e32 v50, v50, v238
	ds_write_b32 v48, v50 offset:104
	v_cndmask_b32_e64 v49, v45, v46, s[46:47]
	v_add_f32_e32 v49, v174, v49
	v_mul_f32_e32 v49, v49, v238
	ds_write_b32 v48, v49 offset:112
	v_cndmask_b32_e64 v50, v46, v47, s[46:47]
	v_add_f32_e32 v50, v175, v50
	v_mul_f32_e32 v50, v50, v238
	ds_write_b32 v48, v50 offset:120

; __device__ __forceinline__ void phase4_attn(const Args& a, LAS unsigned char* lds) {
;     ...
;                     if (i == n_sel - 1 || i == n_all - 1) { const float lt = l_run + __shfl_xor(l_run, 32); const float sc = ((i == n_sel - 1) ? g1 : g2) / fmaxf(lt, 1e-20f);
;                         comb[hkv][0] += oacc[0] * sc; comb[hkv][1] += oacc[1] * sc; oacc[0] = zero16(); oacc[1] = zero16(); l_run = 0.f; }
.Lt2_fin:
	v_mov_b32_e32 v75, v112
	s_nop 1
	v_permlane32_swap_b32 v112, v75
	s_waitcnt lgkmcnt(0)
	v_add_f32_e32 v75, v112, v75
	v_max_f32_e32 v75, 0x1e3ce508, v75
	v_div_scale_f32 v78, s[4:5], v75, v75, v76
	v_rcp_f32_e32 v79, v78
	v_div_scale_f32 v241, vcc, v76, v75, v76
	v_mov_b32_e32 v112, 0
	v_fma_f32 v242, -v78, v79, 1.0
	v_fmac_f32_e32 v79, v242, v79
	v_mul_f32_e32 v242, v241, v79
	v_fma_f32 v243, -v78, v242, v241
	v_fmac_f32_e32 v242, v243, v79
	v_fma_f32 v78, -v78, v242, v241
	v_div_fmas_f32 v78, v78, v79, v242
	v_div_fixup_f32 v76, v78, v75, v76
	v_pk_fma_f32 v[182:183], v[0:1], v[76:77], v[182:183] op_sel_hi:[1,0,1]
	v_pk_fma_f32 v[186:187], v[2:3], v[76:77], v[186:187] op_sel_hi:[1,0,1]
	v_pk_fma_f32 v[180:181], v[4:5], v[76:77], v[180:181] op_sel_hi:[1,0,1]
	v_pk_fma_f32 v[178:179], v[6:7], v[76:77], v[178:179] op_sel_hi:[1,0,1]
	v_pk_fma_f32 v[176:177], v[8:9], v[76:77], v[176:177] op_sel_hi:[1,0,1]
	v_pk_fma_f32 v[174:175], v[10:11], v[76:77], v[174:175] op_sel_hi:[1,0,1]
	v_pk_fma_f32 v[172:173], v[12:13], v[76:77], v[172:173] op_sel_hi:[1,0,1]
	v_pk_fma_f32 v[166:167], v[14:15], v[76:77], v[166:167] op_sel_hi:[1,0,1]
	v_pk_fma_f32 v[168:169], v[16:17], v[76:77], v[168:169] op_sel_hi:[1,0,1]
	v_pk_fma_f32 v[170:171], v[18:19], v[76:77], v[170:171] op_sel_hi:[1,0,1]
	v_pk_fma_f32 v[164:165], v[20:21], v[76:77], v[164:165] op_sel_hi:[1,0,1]
	v_pk_fma_f32 v[162:163], v[22:23], v[76:77], v[162:163] op_sel_hi:[1,0,1]
	v_pk_fma_f32 v[160:161], v[24:25], v[76:77], v[160:161] op_sel_hi:[1,0,1]
	v_pk_fma_f32 v[158:159], v[26:27], v[76:77], v[158:159] op_sel_hi:[1,0,1]
	v_pk_fma_f32 v[156:157], v[28:29], v[76:77], v[156:157] op_sel_hi:[1,0,1]
	v_pk_fma_f32 v[154:155], v[30:31], v[76:77], v[154:155] op_sel_hi:[1,0,1]
	v_mov_b32_e32 v0, 0
	v_mov_b32_e32 v1, 0
	v_mov_b32_e32 v2, 0
	v_mov_b32_e32 v3, 0
	v_mov_b32_e32 v4, 0
	v_mov_b32_e32 v5, 0
	v_mov_b32_e32 v6, 0
	v_mov_b32_e32 v7, 0
	v_mov_b32_e32 v8, 0
	v_mov_b32_e32 v9, 0
	v_mov_b32_e32 v10, 0
	v_mov_b32_e32 v11, 0
	v_mov_b32_e32 v12, 0
	v_mov_b32_e32 v13, 0
	v_mov_b32_e32 v14, 0
	v_mov_b32_e32 v15, 0
	v_mov_b32_e32 v16, 0
	v_mov_b32_e32 v17, 0
	v_mov_b32_e32 v18, 0
	v_mov_b32_e32 v19, 0
	v_mov_b32_e32 v20, 0
	v_mov_b32_e32 v21, 0
	v_mov_b32_e32 v22, 0
	v_mov_b32_e32 v23, 0
	v_mov_b32_e32 v24, 0
	v_mov_b32_e32 v25, 0
	v_mov_b32_e32 v26, 0
	v_mov_b32_e32 v27, 0
	v_mov_b32_e32 v28, 0
	v_mov_b32_e32 v29, 0
	v_mov_b32_e32 v30, 0
	v_mov_b32_e32 v31, 0
	s_branch .Lt2_stage
